# row phases 1 and 7: non-temporal hint on the streamed-once f32 input row loads
# speedup vs baseline: 1.0018x; 1.0018x over previous
.LBB0_204:
	s_cmp_lt_i32 s48, 2
	s_cselect_b64 s[6:7], -1, 0
	s_and_b64 s[6:7], s[6:7], s[4:5]
	v_mov_b32_e32 v18, v190
	s_andn2_b64 vcc, exec, s[6:7]
	s_cbranch_vccnz .LBB0_208
	s_lshl_b32 s4, s3, 3
	s_abs_i32 s5, s4
	v_cvt_f32_u32_e32 v0, s5
	s_sub_i32 s8, 0, s5
	s_ashr_i32 s4, s4, 31
	s_mov_b32 s18, 0
	v_rcp_iflag_f32_e32 v0, v0
	s_nop 0
	v_mul_f32_e32 v0, 0x4f7ffffe, v0
	v_cvt_u32_f32_e32 v0, v0
	s_nop 0
	v_readfirstlane_b32 s9, v0
	s_mul_i32 s8, s8, s9
	s_mul_hi_u32 s8, s9, s8
	s_add_i32 s9, s9, s8
	s_lshr_b32 s8, s9, 17
	s_mul_i32 s9, s8, s5
	s_sub_i32 s9, 0x8000, s9
	s_add_i32 s10, s8, 1
	s_sub_i32 s11, s9, s5
	s_cmp_ge_u32 s9, s5
	s_cselect_b32 s8, s10, s8
	s_cselect_b32 s9, s11, s9
	s_add_i32 s10, s8, 1
	s_cmp_ge_u32 s9, s5
	s_cselect_b32 s5, s10, s8
	s_xor_b32 s5, s5, s4
	s_sub_i32 s17, s5, s4
	s_cmp_lt_i32 s17, 1
	s_cbranch_scc1 .LBB0_208
	s_lshl_b32 s4, s2, 3
	v_readlane_b32 s5, v247, 2
	s_add_i32 s4, s5, s4
	s_mul_i32 s4, s17, s4
	s_ashr_i32 s5, s4, 31
	s_lshr_b32 s8, s5, 19
	s_add_i32 s8, s4, s8
	s_ashr_i32 s8, s8, 13
	s_mulk_i32 s8, 0x1800
	s_ashr_i32 s9, s8, 31
	s_lshl_b64 s[8:9], s[8:9], 2
	s_add_u32 s10, s46, s8
	v_lshlrev_b32_e32 v0, 4, v18
	s_addc_u32 s11, s47, s9
	v_and_b32_e32 v16, 0x3f0, v0
	v_mov_b32_e32 v17, 0
	v_lshl_add_u64 v[0:1], s[10:11], 0, v[16:17]
	s_mov_b32 s12, 0x101000
	s_mov_b64 s[10:11], 0x101000
	v_add_co_u32_e32 v2, vcc, s12, v0
	s_add_u32 s8, s46, s8
	s_nop 0
	v_addc_co_u32_e32 v3, vcc, 0, v1, vcc
	v_lshl_add_u64 v[0:1], v[0:1], 0, s[10:11]
	s_load_dwordx2 s[10:11], s[0:1], 0x28
	s_addc_u32 s9, s47, s9
	global_load_dwordx4 v[20:23], v[2:3], off nt
	global_load_dwordx4 v[24:27], v[0:1], off offset:1024 nt
	global_load_dwordx4 v[28:31], v[0:1], off offset:2048 nt
	global_load_dwordx4 v[32:35], v[0:1], off offset:3072 nt
	s_mov_b32 s12, 0x100000
	v_lshl_add_u64 v[0:1], s[8:9], 0, v[16:17]
	v_add_co_u32_e32 v38, vcc, s12, v0
	s_load_dwordx2 s[12:13], s[0:1], 0x0
	s_waitcnt lgkmcnt(0)
	global_load_dwordx4 v[46:49], v16, s[10:11]
	global_load_dwordx4 v[50:53], v16, s[10:11] offset:1024
	global_load_dwordx4 v[54:57], v16, s[10:11] offset:2048
	global_load_dwordx4 v[58:61], v16, s[10:11] offset:3072
	s_mov_b64 s[10:11], 0x100000
	v_lshl_add_u64 v[36:37], v[0:1], 0, s[10:11]
	v_addc_co_u32_e32 v39, vcc, 0, v1, vcc
	global_load_dwordx4 v[0:3], v[36:37], off offset:1024 nt
	global_load_dwordx4 v[4:7], v[36:37], off offset:2048 nt
	global_load_dwordx4 v[8:11], v[38:39], off nt
	global_load_dwordx4 v[12:15], v[36:37], off offset:3072 nt
	v_mbcnt_lo_u32_b32 v16, -1, 0
	v_mbcnt_hi_u32_b32 v16, -1, v16
	s_add_i32 s14, s4, 1
	v_and_b32_e32 v36, 63, v18
	v_and_b32_e32 v18, 64, v16
	s_ashr_i32 s15, s14, 31
	v_xor_b32_e32 v19, 1, v16
	v_add_u32_e32 v18, 64, v18
	s_lshl_b64 s[8:9], s[14:15], 11
	v_xor_b32_e32 v37, 2, v16
	v_cmp_lt_i32_e32 vcc, v19, v18
	s_add_u32 s8, s46, s8
	v_xor_b32_e32 v38, 4, v16
	v_cndmask_b32_e32 v19, v16, v19, vcc
	v_cmp_lt_i32_e32 vcc, v37, v18
	s_addc_u32 s9, s47, s9
	s_lshl_b64 s[10:11], s[4:5], 12
	v_xor_b32_e32 v39, 8, v16
	v_cndmask_b32_e32 v42, v16, v37, vcc
	v_cmp_lt_i32_e32 vcc, v38, v18
	s_add_u32 s10, s12, s10
	v_xor_b32_e32 v40, 16, v16
	v_cndmask_b32_e32 v38, v16, v38, vcc
	v_cmp_lt_i32_e32 vcc, v39, v18
	s_addc_u32 s11, s13, s11
	s_lshl_b64 s[14:15], s[14:15], 12
	v_xor_b32_e32 v41, 32, v16
	v_cndmask_b32_e32 v39, v16, v39, vcc
	v_cmp_lt_i32_e32 vcc, v40, v18
	s_add_u32 s12, s12, s14
	s_addc_u32 s13, s13, s15
	v_cndmask_b32_e32 v43, v16, v40, vcc
	v_cmp_lt_i32_e32 vcc, v41, v18
	s_lshl_b64 s[4:5], s[4:5], 11
	v_lshlrev_b32_e32 v37, 2, v19
	v_cndmask_b32_e32 v16, v16, v41, vcc
	s_add_u32 s14, s46, s4
	v_lshlrev_b32_e32 v40, 2, v42
	v_lshlrev_b32_e32 v41, 2, v38
	v_lshlrev_b32_e32 v42, 2, v39
	v_lshlrev_b32_e32 v43, 2, v43
	v_lshlrev_b32_e32 v44, 2, v16
	v_lshlrev_b32_e32 v16, 3, v36
	s_addc_u32 s15, s47, s5
	s_mov_b32 s16, 0x3a800000
	s_mov_b32 s19, 0x800000
	s_brev_b32 s20, 16
	s_waitcnt vmcnt(10)
	v_pk_add_f32 v[24:25], v[24:25], 1.0 op_sel_hi:[1,0]
	v_pk_add_f32 v[18:19], v[22:23], 1.0 op_sel_hi:[1,0]
	v_pk_add_f32 v[20:21], v[20:21], 1.0 op_sel_hi:[1,0]
	v_pk_add_f32 v[22:23], v[26:27], 1.0 op_sel_hi:[1,0]
	s_waitcnt vmcnt(9)
	v_pk_add_f32 v[26:27], v[30:31], 1.0 op_sel_hi:[1,0]
	v_pk_add_f32 v[28:29], v[28:29], 1.0 op_sel_hi:[1,0]
	s_waitcnt vmcnt(8)
	v_pk_add_f32 v[30:31], v[34:35], 1.0 op_sel_hi:[1,0]
	v_pk_add_f32 v[32:33], v[32:33], 1.0 op_sel_hi:[1,0]
	s_waitcnt vmcnt(7)
	v_pk_mul_f32 v[18:19], v[48:49], v[18:19]
	v_pk_mul_f32 v[20:21], v[46:47], v[20:21]
	s_waitcnt vmcnt(6)
	v_pk_mul_f32 v[22:23], v[52:53], v[22:23]
	v_pk_mul_f32 v[24:25], v[50:51], v[24:25]
	s_waitcnt vmcnt(5)
	v_pk_mul_f32 v[26:27], v[56:57], v[26:27]
	v_pk_mul_f32 v[28:29], v[54:55], v[28:29]
	s_waitcnt vmcnt(4)
	v_pk_mul_f32 v[30:31], v[60:61], v[30:31]
	v_pk_mul_f32 v[32:33], v[58:59], v[32:33]
	v_lshlrev_b32_e32 v34, 4, v36
	v_mov_b32_e32 v35, v17
	v_mov_b32_e32 v36, 0x358637bd
.LBB0_207:
	v_lshl_add_u64 v[38:39], s[10:11], 0, v[34:35]
	v_lshl_add_u64 v[78:79], s[12:13], 0, v[34:35]
	global_load_dwordx4 v[46:49], v[38:39], off nt
	global_load_dwordx4 v[50:53], v[38:39], off offset:1024 nt
	global_load_dwordx4 v[54:57], v[38:39], off offset:3072 nt
	global_load_dwordx4 v[58:61], v[38:39], off offset:2048 nt
	global_load_dwordx4 v[62:65], v[78:79], off nt
	global_load_dwordx4 v[66:69], v[78:79], off offset:1024 nt
	global_load_dwordx4 v[70:73], v[78:79], off offset:3072 nt
	global_load_dwordx4 v[74:77], v[78:79], off offset:2048 nt
	v_lshl_add_u64 v[80:81], s[14:15], 0, v[16:17]
	v_add_co_u32_e32 v38, vcc, s20, v80
	v_lshl_add_u64 v[82:83], s[8:9], 0, v[16:17]
	s_nop 0
	v_addc_co_u32_e32 v39, vcc, 0, v81, vcc
	v_add_co_u32_e32 v78, vcc, s20, v82
	s_add_i32 s18, s18, 2
	s_nop 0
	v_addc_co_u32_e32 v79, vcc, 0, v83, vcc
	s_add_u32 s8, s8, 0x1000
	s_addc_u32 s9, s9, 0
	s_add_u32 s10, s10, 0x2000
	s_addc_u32 s11, s11, 0
	s_add_u32 s12, s12, 0x2000
	s_addc_u32 s13, s13, 0
	s_add_u32 s14, s14, 0x1000
	s_addc_u32 s15, s15, 0
	s_cmp_lt_i32 s18, s17
	s_waitcnt vmcnt(7)
	v_pk_mul_f32 v[80:81], v[48:49], v[48:49]
	v_pk_mul_f32 v[82:83], v[46:47], v[46:47]
	s_waitcnt vmcnt(6)
	v_pk_mul_f32 v[84:85], v[52:53], v[52:53]
	v_pk_mul_f32 v[86:87], v[50:51], v[50:51]
	s_waitcnt vmcnt(4)
	v_mul_f32_e32 v88, v59, v59
	v_mul_f32_e32 v90, v61, v61
	s_waitcnt vmcnt(3)
	v_pk_mul_f32 v[92:93], v[64:65], v[64:65]
	v_pk_mul_f32 v[94:95], v[62:63], v[62:63]
	s_waitcnt vmcnt(2)
	v_pk_mul_f32 v[96:97], v[68:69], v[68:69]
	v_pk_mul_f32 v[98:99], v[66:67], v[66:67]
	v_mul_f32_e32 v106, v56, v56
	v_mul_f32_e32 v107, v57, v57
	v_pk_mov_b32 v[104:105], v[82:83], v[80:81] op_sel:[1,0]
	v_mov_b32_e32 v83, v81
	v_pk_mov_b32 v[80:81], v[86:87], v[84:85] op_sel:[1,0]
	v_mov_b32_e32 v87, v85
	v_pk_fma_f32 v[84:85], v[58:59], v[58:59], v[88:89] op_sel_hi:[1,1,0]
	v_pk_fma_f32 v[88:89], v[60:61], v[60:61], v[90:91] op_sel_hi:[1,1,0]
	v_pk_mov_b32 v[90:91], v[94:95], v[92:93] op_sel:[1,0]
	v_mov_b32_e32 v95, v93
	v_pk_mov_b32 v[92:93], v[98:99], v[96:97] op_sel:[1,0]
	v_mov_b32_e32 v99, v97
	v_mul_f32_e32 v103, v55, v55
	s_waitcnt vmcnt(0)
	v_mul_f32_e32 v100, v75, v75
	v_mul_f32_e32 v102, v77, v77
	v_pk_add_f32 v[82:83], v[104:105], v[82:83]
	v_pk_add_f32 v[80:81], v[80:81], v[86:87]
	v_mov_b32_e32 v85, v106
	v_mov_b32_e32 v89, v107
	v_pk_add_f32 v[86:87], v[90:91], v[94:95]
	v_pk_add_f32 v[90:91], v[92:93], v[98:99]
	v_mul_f32_e32 v45, v54, v54
	v_mul_f32_e32 v108, v70, v70
	v_mul_f32_e32 v109, v71, v71
	v_mul_f32_e32 v110, v72, v72
	v_mul_f32_e32 v111, v73, v73
	v_pk_fma_f32 v[96:97], v[74:75], v[74:75], v[100:101] op_sel_hi:[1,1,0]
	v_pk_fma_f32 v[100:101], v[76:77], v[76:77], v[102:103] op_sel_hi:[1,1,0]
	v_pk_add_f32 v[82:83], v[82:83], v[82:83] op_sel:[0,1] op_sel_hi:[1,0]
	v_pk_add_f32 v[80:81], v[80:81], v[80:81] op_sel:[0,1] op_sel_hi:[1,0]
	v_pk_add_f32 v[84:85], v[84:85], v[88:89]
	v_pk_add_f32 v[86:87], v[86:87], v[86:87] op_sel:[0,1] op_sel_hi:[1,0]
	v_pk_add_f32 v[88:89], v[90:91], v[90:91] op_sel:[0,1] op_sel_hi:[1,0]
	v_mov_b32_e32 v97, v110
	v_mov_b32_e32 v101, v111
	v_mov_b32_e32 v83, v45
	v_mov_b32_e32 v81, v103
	v_mov_b32_e32 v87, v108
	v_mov_b32_e32 v89, v109
	v_pk_add_f32 v[90:91], v[96:97], v[100:101]
	v_pk_add_f32 v[80:81], v[82:83], v[80:81]
	v_pk_add_f32 v[82:83], v[86:87], v[88:89]
	v_pk_add_f32 v[80:81], v[80:81], v[84:85]
	v_pk_add_f32 v[82:83], v[82:83], v[90:91]
	v_mov_b32_e32 v85, v80
	v_mov_b32_e32 v84, v82
	v_mov_b32_e32 v80, v83
	v_pk_add_f32 v[80:81], v[84:85], v[80:81]
	ds_bpermute_b32 v83, v37, v81
	ds_bpermute_b32 v82, v37, v80
	s_waitcnt lgkmcnt(0)
	v_pk_add_f32 v[80:81], v[80:81], v[82:83]
	ds_bpermute_b32 v83, v40, v81
	ds_bpermute_b32 v82, v40, v80
	s_waitcnt lgkmcnt(0)
	v_pk_add_f32 v[80:81], v[80:81], v[82:83]
	ds_bpermute_b32 v83, v41, v81
	ds_bpermute_b32 v82, v41, v80
	s_waitcnt lgkmcnt(0)
	v_pk_add_f32 v[80:81], v[80:81], v[82:83]
	ds_bpermute_b32 v83, v42, v81
	ds_bpermute_b32 v82, v42, v80
	s_waitcnt lgkmcnt(0)
	v_pk_add_f32 v[80:81], v[80:81], v[82:83]
	ds_bpermute_b32 v83, v43, v81
	ds_bpermute_b32 v82, v43, v80
	s_waitcnt lgkmcnt(0)
	v_pk_add_f32 v[80:81], v[80:81], v[82:83]
	ds_bpermute_b32 v83, v44, v81
	ds_bpermute_b32 v82, v44, v80
	s_waitcnt lgkmcnt(0)
	v_pk_add_f32 v[80:81], v[80:81], v[82:83]
	s_nop 0
	v_pk_fma_f32 v[80:81], v[80:81], s[16:17], v[36:37] op_sel_hi:[1,0,0]
	s_nop 0
	v_mul_f32_e32 v45, 0x4b800000, v81
	v_cmp_gt_f32_e64 s[4:5], s19, v81
	v_mul_f32_e32 v82, 0x4b800000, v80
	v_cmp_gt_f32_e32 vcc, s19, v80
	v_cndmask_b32_e64 v45, v81, v45, s[4:5]
	v_rsq_f32_e32 v45, v45
	v_cndmask_b32_e32 v80, v80, v82, vcc
	v_rsq_f32_e32 v81, v80
	v_mul_f32_e32 v80, 0x45800000, v45
	v_cndmask_b32_e64 v80, v45, v80, s[4:5]
	v_mul_f32_e32 v82, 0x45800000, v81
	v_cndmask_b32_e32 v82, v81, v82, vcc
	v_pk_mul_f32 v[46:47], v[46:47], v[80:81] op_sel_hi:[1,0]
	v_pk_mul_f32 v[48:49], v[48:49], v[80:81] op_sel_hi:[1,0]
	v_pk_mul_f32 v[50:51], v[50:51], v[80:81] op_sel_hi:[1,0]
	v_pk_mul_f32 v[52:53], v[52:53], v[80:81] op_sel_hi:[1,0]
	v_pk_mul_f32 v[58:59], v[58:59], v[80:81] op_sel_hi:[1,0]
	v_pk_mul_f32 v[60:61], v[60:61], v[80:81] op_sel_hi:[1,0]
	v_pk_mul_f32 v[54:55], v[54:55], v[80:81] op_sel_hi:[1,0]
	v_pk_mul_f32 v[56:57], v[56:57], v[80:81] op_sel_hi:[1,0]
	v_pk_mul_f32 v[62:63], v[62:63], v[82:83] op_sel_hi:[1,0]
	v_pk_mul_f32 v[64:65], v[64:65], v[82:83] op_sel_hi:[1,0]
	v_pk_mul_f32 v[66:67], v[66:67], v[82:83] op_sel_hi:[1,0]
	v_pk_mul_f32 v[68:69], v[68:69], v[82:83] op_sel_hi:[1,0]
	v_pk_mul_f32 v[74:75], v[74:75], v[82:83] op_sel_hi:[1,0]
	v_pk_mul_f32 v[76:77], v[76:77], v[82:83] op_sel_hi:[1,0]
	v_pk_mul_f32 v[70:71], v[70:71], v[82:83] op_sel_hi:[1,0]
	v_pk_mul_f32 v[72:73], v[72:73], v[82:83] op_sel_hi:[1,0]
	v_pk_fma_f32 v[48:49], v[18:19], v[48:49], v[10:11]
	v_pk_fma_f32 v[46:47], v[20:21], v[46:47], v[8:9]
	v_pk_fma_f32 v[52:53], v[22:23], v[52:53], v[2:3]
	v_pk_fma_f32 v[50:51], v[24:25], v[50:51], v[0:1]
	v_pk_fma_f32 v[60:61], v[26:27], v[60:61], v[6:7]
	v_pk_fma_f32 v[58:59], v[28:29], v[58:59], v[4:5]
	v_pk_fma_f32 v[56:57], v[30:31], v[56:57], v[14:15]
	v_pk_fma_f32 v[54:55], v[32:33], v[54:55], v[12:13]
	v_pk_fma_f32 v[64:65], v[18:19], v[64:65], v[10:11]
	v_pk_fma_f32 v[62:63], v[20:21], v[62:63], v[8:9]
	v_pk_fma_f32 v[68:69], v[22:23], v[68:69], v[2:3]
	v_pk_fma_f32 v[66:67], v[24:25], v[66:67], v[0:1]
	v_pk_fma_f32 v[76:77], v[26:27], v[76:77], v[6:7]
	v_pk_fma_f32 v[74:75], v[28:29], v[74:75], v[4:5]
	v_pk_fma_f32 v[72:73], v[30:31], v[72:73], v[14:15]
	v_pk_fma_f32 v[70:71], v[32:33], v[70:71], v[12:13]
	v_cvt_pk_bf16_f32 v46, v46, v47
	v_cvt_pk_bf16_f32 v47, v48, v49
	v_cvt_pk_bf16_f32 v48, v50, v51
	v_cvt_pk_bf16_f32 v49, v52, v53
	v_cvt_pk_bf16_f32 v50, v58, v59
	v_cvt_pk_bf16_f32 v51, v60, v61
	v_cvt_pk_bf16_f32 v52, v54, v55
	v_cvt_pk_bf16_f32 v53, v56, v57
	v_cvt_pk_bf16_f32 v54, v62, v63
	v_cvt_pk_bf16_f32 v55, v64, v65
	v_cvt_pk_bf16_f32 v56, v66, v67
	v_cvt_pk_bf16_f32 v57, v68, v69
	v_cvt_pk_bf16_f32 v58, v74, v75
	v_cvt_pk_bf16_f32 v59, v76, v77
	v_cvt_pk_bf16_f32 v60, v70, v71
	v_cvt_pk_bf16_f32 v61, v72, v73
	global_store_dwordx2 v[38:39], v[46:47], off
	global_store_dwordx2 v[38:39], v[48:49], off offset:512
	global_store_dwordx2 v[38:39], v[50:51], off offset:1024
	global_store_dwordx2 v[38:39], v[52:53], off offset:1536
	global_store_dwordx2 v[78:79], v[54:55], off
	global_store_dwordx2 v[78:79], v[56:57], off offset:512
	global_store_dwordx2 v[78:79], v[58:59], off offset:1024
	global_store_dwordx2 v[78:79], v[60:61], off offset:1536
	s_cbranch_scc1 .LBB0_207

.LBB0_761:
	s_cmp_lt_i32 s48, 8
	s_cselect_b64 s[6:7], -1, 0
	s_and_b64 s[6:7], s[6:7], s[4:5]
	s_waitcnt vmcnt(0)
	v_mov_b32_e32 v16, v190
	s_andn2_b64 vcc, exec, s[6:7]
	s_cbranch_vccnz .LBB0_765
	s_lshl_b32 s4, s3, 3
	s_abs_i32 s5, s4
	v_cvt_f32_u32_e32 v0, s5
	s_sub_i32 s8, 0, s5
	s_ashr_i32 s4, s4, 31
	s_mov_b32 s22, 0
	v_rcp_iflag_f32_e32 v0, v0
	s_nop 0
	v_mul_f32_e32 v0, 0x4f7ffffe, v0
	v_cvt_u32_f32_e32 v0, v0
	s_nop 0
	v_readfirstlane_b32 s9, v0
	s_mul_i32 s8, s8, s9
	s_mul_hi_u32 s8, s9, s8
	s_add_i32 s9, s9, s8
	s_lshr_b32 s8, s9, 17
	s_mul_i32 s9, s8, s5
	s_sub_i32 s9, 0x8000, s9
	s_add_i32 s10, s8, 1
	s_sub_i32 s11, s9, s5
	s_cmp_ge_u32 s9, s5
	s_cselect_b32 s8, s10, s8
	s_cselect_b32 s9, s11, s9
	s_add_i32 s10, s8, 1
	s_cmp_ge_u32 s9, s5
	s_cselect_b32 s5, s10, s8
	s_xor_b32 s5, s5, s4
	s_sub_i32 s21, s5, s4
	s_cmp_lt_i32 s21, 1
	s_cbranch_scc1 .LBB0_765
	s_load_dwordx2 s[4:5], s[0:1], 0x28
	s_load_dwordx2 s[18:19], s[0:1], 0x0
	v_lshlrev_b32_e32 v0, 4, v16
	v_and_b32_e32 v32, 0x3f0, v0
	v_mov_b32_e32 v33, 0
	s_waitcnt lgkmcnt(0)
	s_add_u32 s8, s4, 0x1000
	s_addc_u32 s9, s5, 0
	s_add_u32 s10, s4, 0x2000
	s_addc_u32 s11, s5, 0
	s_lshl_b32 s4, s2, 3
	v_readlane_b32 s5, v247, 2
	s_add_i32 s4, s5, s4
	s_mul_i32 s4, s21, s4
	s_ashr_i32 s5, s4, 31
	s_lshr_b32 s12, s5, 19
	s_add_i32 s12, s4, s12
	s_ashr_i32 s12, s12, 13
	s_mul_hi_i32 s13, s12, 0x6000
	s_mulk_i32 s12, 0x6000
	s_add_u32 s12, s46, s12
	s_addc_u32 s13, s47, s13
	v_lshl_add_u64 v[0:1], s[12:13], 0, v[32:33]
	s_mov_b64 s[12:13], 0x102000
	v_lshl_add_u64 v[2:3], v[0:1], 0, s[12:13]
	s_mov_b32 s12, 0x103000
	v_add_co_u32_e32 v30, vcc, s12, v0
	s_mov_b64 s[12:13], 0x104000
	s_nop 0
	v_addc_co_u32_e32 v31, vcc, 0, v1, vcc
	v_lshl_add_u64 v[4:5], v[0:1], 0, s[12:13]
	s_mov_b32 s12, 0x104000
	v_add_co_u32_e32 v6, vcc, s12, v0
	global_load_dwordx4 v[18:21], v[30:31], off offset:-4096 nt
	global_load_dwordx4 v[22:25], v32, s[8:9]
	v_addc_co_u32_e32 v7, vcc, 0, v1, vcc
	global_load_dwordx4 v[26:29], v[6:7], off nt
	global_load_dwordx4 v[40:43], v[2:3], off offset:1024 nt
	v_or_b32_e32 v6, 0x400, v32
	global_load_dwordx4 v[44:47], v6, s[8:9]
	global_load_dwordx4 v[48:51], v[4:5], off offset:1024 nt
	global_load_dwordx4 v[52:55], v[2:3], off offset:2048 nt
	v_or_b32_e32 v7, 0x800, v32
	global_load_dwordx4 v[56:59], v7, s[8:9]
	global_load_dwordx4 v[60:63], v[4:5], off offset:2048 nt
	global_load_dwordx4 v[64:67], v[2:3], off offset:3072 nt
	v_or_b32_e32 v2, 0xc00, v32
	global_load_dwordx4 v[70:73], v2, s[8:9]
	global_load_dwordx4 v[74:77], v[4:5], off offset:3072 nt
	global_load_dwordx4 v[78:81], v32, s[10:11]
	global_load_dwordx4 v[82:85], v6, s[10:11]
	global_load_dwordx4 v[86:89], v7, s[10:11]
	global_load_dwordx4 v[90:93], v2, s[10:11]
	s_mov_b64 s[8:9], 0x103000
	v_lshl_add_u64 v[34:35], v[0:1], 0, s[8:9]
	global_load_dwordx4 v[0:3], v[30:31], off nt
	global_load_dwordx4 v[4:7], v[34:35], off offset:1024 nt
	global_load_dwordx4 v[8:11], v[34:35], off offset:2048 nt
	global_load_dwordx4 v[12:15], v[34:35], off offset:3072 nt
	v_mbcnt_lo_u32_b32 v17, -1, 0
	v_mbcnt_hi_u32_b32 v17, -1, v17
	v_and_b32_e32 v30, 64, v17
	v_xor_b32_e32 v31, 1, v17
	v_add_u32_e32 v68, 64, v30
	s_add_i32 s14, s4, 1
	v_xor_b32_e32 v32, 2, v17
	v_cmp_lt_i32_e32 vcc, v31, v68
	s_ashr_i32 s15, s14, 31
	s_lshl_b64 s[12:13], s[14:15], 11
	v_cndmask_b32_e32 v30, v17, v31, vcc
	v_cmp_lt_i32_e32 vcc, v32, v68
	s_add_u32 s8, s46, s12
	s_addc_u32 s9, s47, s13
	v_cndmask_b32_e32 v32, v17, v32, vcc
	s_lshl_b64 s[16:17], s[4:5], 11
	s_add_u32 s10, s46, s16
	s_addc_u32 s11, s47, s17
	s_add_u32 s12, s38, s12
	s_addc_u32 s13, s39, s13
	s_lshl_b64 s[14:15], s[14:15], 12
	s_add_u32 s14, s18, s14
	s_addc_u32 s15, s19, s15
	s_add_u32 s16, s38, s16
	s_addc_u32 s17, s39, s17
	s_lshl_b64 s[4:5], s[4:5], 12
	v_lshlrev_b32_e32 v69, 2, v30
	v_and_b32_e32 v16, 63, v16
	s_add_u32 s18, s18, s4
	s_addc_u32 s19, s19, s5
	s_brev_b32 s23, 32
	s_mov_b32 s20, 0x3a800000
	s_mov_b32 s24, 0x800000
	s_brev_b32 s25, 16
	s_waitcnt vmcnt(18)
	v_pk_mul_f32 v[36:37], v[18:19], v[22:23]
	v_pk_mul_f32 v[34:35], v[20:21], v[24:25]
	s_waitcnt vmcnt(17)
	v_pk_add_f32 v[18:19], v[28:29], 1.0 op_sel_hi:[1,0]
	s_waitcnt vmcnt(15)
	v_pk_mul_f32 v[40:41], v[40:41], v[44:45]
	s_waitcnt vmcnt(14)
	v_pk_add_f32 v[22:23], v[50:51], 1.0 op_sel_hi:[1,0]
	v_pk_add_f32 v[24:25], v[48:49], 1.0 op_sel_hi:[1,0]
	s_waitcnt vmcnt(7)
	v_pk_mul_f32 v[50:51], v[80:81], v[18:19]
	v_xor_b32_e32 v18, 4, v17
	v_cmp_lt_i32_e32 vcc, v18, v68
	v_pk_mul_f32 v[44:45], v[52:53], v[56:57]
	s_waitcnt vmcnt(6)
	v_pk_mul_f32 v[56:57], v[82:83], v[24:25]
	v_cndmask_b32_e32 v18, v17, v18, vcc
	v_lshlrev_b32_e32 v81, 2, v18
	v_xor_b32_e32 v18, 8, v17
	v_cmp_lt_i32_e32 vcc, v18, v68
	v_pk_add_f32 v[20:21], v[26:27], 1.0 op_sel_hi:[1,0]
	v_pk_add_f32 v[26:27], v[62:63], 1.0 op_sel_hi:[1,0]
	v_cndmask_b32_e32 v18, v17, v18, vcc
	v_lshlrev_b32_e32 v82, 2, v18
	v_xor_b32_e32 v18, 16, v17
	v_cmp_lt_i32_e32 vcc, v18, v68
	v_pk_add_f32 v[28:29], v[60:61], 1.0 op_sel_hi:[1,0]
	v_pk_mul_f32 v[48:49], v[64:65], v[70:71]
	v_cndmask_b32_e32 v18, v17, v18, vcc
	v_lshlrev_b32_e32 v83, 2, v18
	v_xor_b32_e32 v18, 32, v17
	v_cmp_lt_i32_e32 vcc, v18, v68
	v_pk_add_f32 v[30:31], v[76:77], 1.0 op_sel_hi:[1,0]
	v_pk_add_f32 v[64:65], v[74:75], 1.0 op_sel_hi:[1,0]
	v_cndmask_b32_e32 v17, v17, v18, vcc
	v_pk_mul_f32 v[38:39], v[42:43], v[46:47]
	v_pk_mul_f32 v[42:43], v[54:55], v[58:59]
	v_pk_mul_f32 v[46:47], v[66:67], v[72:73]
	v_pk_mul_f32 v[52:53], v[78:79], v[20:21]
	v_pk_mul_f32 v[54:55], v[84:85], v[22:23]
	s_waitcnt vmcnt(5)
	v_pk_mul_f32 v[58:59], v[88:89], v[26:27]
	v_pk_mul_f32 v[60:61], v[86:87], v[28:29]
	s_waitcnt vmcnt(4)
	v_pk_mul_f32 v[62:63], v[92:93], v[30:31]
	v_pk_mul_f32 v[64:65], v[90:91], v[64:65]
	v_lshlrev_b32_e32 v80, 2, v32
	v_lshlrev_b32_e32 v84, 2, v17
	v_lshlrev_b32_e32 v32, 3, v16
	v_lshlrev_b32_e32 v66, 4, v16
	v_mov_b32_e32 v67, v33
	v_mov_b32_e32 v68, 0x358637bd
.LBB0_764:
	v_lshl_add_u64 v[74:75], s[8:9], 0, v[32:33]
	v_lshl_add_u64 v[72:73], s[10:11], 0, v[32:33]
	v_add_co_u32_e64 v104, s[4:5], s23, v74
	v_lshl_add_u64 v[16:17], s[18:19], 0, v[66:67]
	v_lshl_add_u64 v[76:77], s[14:15], 0, v[66:67]
	v_add_co_u32_e32 v102, vcc, 0x4000000, v72
	v_addc_co_u32_e64 v105, s[4:5], 0, v75, s[4:5]
	global_load_dwordx4 v[86:89], v[16:17], off nt
	global_load_dwordx4 v[90:93], v[16:17], off offset:1024 nt
	global_load_dwordx4 v[94:97], v[16:17], off offset:2048 nt
	global_load_dwordx4 v[98:101], v[16:17], off offset:3072 nt
	global_load_dwordx4 v[28:31], v[76:77], off nt
	global_load_dwordx4 v[24:27], v[76:77], off offset:1024 nt
	global_load_dwordx4 v[20:23], v[76:77], off offset:2048 nt
	s_nop 0
	global_load_dwordx4 v[16:19], v[76:77], off offset:3072 nt
	v_add_co_u32_e64 v76, s[4:5], s25, v72
	v_addc_co_u32_e32 v103, vcc, 0, v73, vcc
	s_nop 0
	v_addc_co_u32_e64 v77, s[4:5], 0, v73, s[4:5]
	global_load_dwordx2 v[106:107], v[104:105], off offset:1536
	global_load_dwordx2 v[108:109], v[104:105], off
	global_load_dwordx2 v[110:111], v[104:105], off offset:512
	global_load_dwordx2 v[112:113], v[104:105], off offset:1024
	global_load_dwordx2 v[72:73], v[102:103], off offset:1536
	s_nop 0
	global_load_dwordx2 v[104:105], v[102:103], off
	global_load_dwordx2 v[114:115], v[102:103], off offset:512
	global_load_dwordx2 v[116:117], v[102:103], off offset:1024
	v_lshl_add_u64 v[70:71], s[16:17], 0, v[32:33]
	v_add_co_u32_e64 v74, s[4:5], s25, v74
	v_lshl_add_u64 v[78:79], s[12:13], 0, v[32:33]
	s_nop 0
	v_addc_co_u32_e64 v75, s[4:5], 0, v75, s[4:5]
	s_add_i32 s22, s22, 2
	s_add_u32 s8, s8, 0x1000
	s_addc_u32 s9, s9, 0
	s_add_u32 s10, s10, 0x1000
	s_addc_u32 s11, s11, 0
	s_add_u32 s12, s12, 0x1000
	s_addc_u32 s13, s13, 0
	s_add_u32 s14, s14, 0x2000
	s_addc_u32 s15, s15, 0
	s_add_u32 s16, s16, 0x1000
	s_addc_u32 s17, s17, 0
	s_add_u32 s18, s18, 0x2000
	s_addc_u32 s19, s19, 0
	s_cmp_lt_i32 s22, s21
	s_waitcnt vmcnt(7)
	v_lshlrev_b32_e32 v103, 16, v106
	s_waitcnt vmcnt(6)
	v_lshlrev_b32_e32 v120, 16, v108
	v_and_b32_e32 v121, 0xffff0000, v108
	v_lshlrev_b32_e32 v108, 16, v109
	v_and_b32_e32 v109, 0xffff0000, v109
	s_waitcnt vmcnt(5)
	v_lshlrev_b32_e32 v123, 16, v111
	v_lshlrev_b32_e32 v122, 16, v110
	v_and_b32_e32 v111, 0xffff0000, v111
	v_and_b32_e32 v110, 0xffff0000, v110
	s_waitcnt vmcnt(2)
	v_lshlrev_b32_e32 v130, 16, v104
	v_and_b32_e32 v131, 0xffff0000, v104
	v_lshlrev_b32_e32 v104, 16, v105
	v_and_b32_e32 v105, 0xffff0000, v105
	s_waitcnt vmcnt(1)
	v_lshlrev_b32_e32 v133, 16, v115
	v_lshlrev_b32_e32 v132, 16, v114
	v_and_b32_e32 v115, 0xffff0000, v115
	v_and_b32_e32 v114, 0xffff0000, v114
	v_lshlrev_b32_e32 v124, 16, v112
	v_and_b32_e32 v125, 0xffff0000, v112
	v_lshlrev_b32_e32 v112, 16, v113
	v_and_b32_e32 v113, 0xffff0000, v113
	v_lshlrev_b32_e32 v127, 16, v72
	v_mul_f32_e32 v102, v109, v109
	v_pk_mul_f32 v[136:137], v[110:111], v[110:111]
	v_mul_f32_e32 v126, v121, v121
	v_mul_f32_e32 v144, v105, v105
	v_pk_mul_f32 v[146:147], v[114:115], v[114:115]
	v_mul_f32_e32 v148, v131, v131
	v_and_b32_e32 v119, 0xffff0000, v106
	v_lshlrev_b32_e32 v106, 16, v107
	s_waitcnt vmcnt(0)
	v_lshlrev_b32_e32 v134, 16, v116
	v_and_b32_e32 v135, 0xffff0000, v116
	v_lshlrev_b32_e32 v116, 16, v117
	v_and_b32_e32 v117, 0xffff0000, v117
	v_mov_b32_e32 v139, v103
	v_mul_f32_e32 v138, v125, v125
	v_mul_f32_e32 v140, v113, v113
	v_mov_b32_e32 v142, v122
	v_mov_b32_e32 v143, v110
	v_mov_b32_e32 v110, v123
	v_mov_b32_e32 v141, v127
	v_mov_b32_e32 v154, v132
	v_mov_b32_e32 v155, v114
	v_mov_b32_e32 v114, v133
	v_pk_fma_f32 v[156:157], v[108:109], v[108:109], v[102:103] op_sel_hi:[1,1,0]
	v_pk_fma_f32 v[122:123], v[122:123], v[122:123], v[136:137]
	v_pk_fma_f32 v[136:137], v[120:121], v[120:121], v[126:127] op_sel_hi:[1,1,0]
	v_pk_fma_f32 v[144:145], v[104:105], v[104:105], v[144:145] op_sel_hi:[1,1,0]
	v_pk_fma_f32 v[132:133], v[132:133], v[132:133], v[146:147]
	v_pk_fma_f32 v[146:147], v[130:131], v[130:131], v[148:149] op_sel_hi:[1,1,0]
	v_and_b32_e32 v129, 0xffff0000, v72
	v_lshlrev_b32_e32 v72, 16, v73
	v_and_b32_e32 v73, 0xffff0000, v73
	v_mul_f32_e32 v153, v106, v106
	v_mul_f32_e32 v150, v135, v135
	v_mul_f32_e32 v152, v117, v117
	v_pk_fma_f32 v[158:159], v[124:125], v[124:125], v[138:139] op_sel_hi:[1,1,0]
	v_pk_fma_f32 v[160:161], v[112:113], v[112:113], v[140:141] op_sel_hi:[1,1,0]
	v_mov_b32_e32 v102, v136
	v_mov_b32_e32 v138, v156
	v_mov_b32_e32 v126, v146
	v_mov_b32_e32 v140, v144
	v_and_b32_e32 v107, 0xffff0000, v107
	v_mul_f32_e32 v85, v119, v119
	v_mov_b32_e32 v118, v103
	v_mul_f32_e32 v163, v129, v129
	v_mul_f32_e32 v164, v72, v72
	v_mul_f32_e32 v165, v73, v73
	v_mov_b32_e32 v128, v127
	v_pk_fma_f32 v[148:149], v[134:135], v[134:135], v[150:151] op_sel_hi:[1,1,0]
	v_pk_fma_f32 v[150:151], v[116:117], v[116:117], v[152:153] op_sel_hi:[1,1,0]
	v_pk_add_f32 v[136:137], v[136:137], v[156:157]
	v_pk_add_f32 v[122:123], v[122:123], v[122:123] op_sel:[0,1] op_sel_hi:[1,0]
	v_pk_add_f32 v[144:145], v[146:147], v[144:145]
	v_pk_add_f32 v[132:133], v[132:133], v[132:133] op_sel:[0,1] op_sel_hi:[1,0]
	v_pk_mul_f32 v[102:103], v[102:103], v[138:139]
	v_pk_mul_f32 v[126:127], v[126:127], v[140:141]
	v_mul_f32_e32 v162, v107, v107
	v_mov_b32_e32 v149, v164
	v_mov_b32_e32 v151, v165
	v_mov_b32_e32 v123, v85
	v_mov_b32_e32 v133, v163
	v_mov_b32_e32 v137, v103
	v_mov_b32_e32 v145, v127
	v_mov_b32_e32 v159, v153
	v_mov_b32_e32 v161, v162
	v_pk_add_f32 v[140:141], v[148:149], v[150:151]
	v_pk_add_f32 v[102:103], v[136:137], v[122:123]
	v_pk_add_f32 v[122:123], v[144:145], v[132:133]
	v_pk_add_f32 v[138:139], v[158:159], v[160:161]
	v_pk_add_f32 v[122:123], v[122:123], v[140:141]
	v_pk_add_f32 v[102:103], v[102:103], v[138:139]
	v_add_f32_e32 v85, v122, v123
	v_mov_b32_e32 v126, v102
	ds_bpermute_b32 v102, v69, v85
	s_waitcnt lgkmcnt(0)
	v_add_f32_e32 v85, v85, v102
	ds_bpermute_b32 v102, v80, v85
	s_waitcnt lgkmcnt(0)
	v_add_f32_e32 v85, v85, v102
	ds_bpermute_b32 v102, v81, v85
	s_waitcnt lgkmcnt(0)
	v_add_f32_e32 v85, v85, v102
	ds_bpermute_b32 v102, v82, v85
	s_waitcnt lgkmcnt(0)
	v_add_f32_e32 v85, v85, v102
	ds_bpermute_b32 v102, v83, v85
	s_waitcnt lgkmcnt(0)
	v_add_f32_e32 v85, v85, v102
	ds_bpermute_b32 v102, v84, v85
	s_waitcnt lgkmcnt(0)
	v_add_f32_e32 v85, v85, v102
	v_fmamk_f32 v85, v85, 0x3a800000, v68
	v_mul_f32_e32 v102, 0x4b800000, v85
	v_cmp_gt_f32_e32 vcc, s24, v85
	s_nop 1
	v_cndmask_b32_e32 v85, v85, v102, vcc
	v_rsq_f32_e32 v85, v85
	s_nop 0
	v_mul_f32_e32 v102, 0x45800000, v85
	v_cndmask_b32_e32 v102, v85, v102, vcc
	v_pk_mul_f32 v[122:123], v[102:103], v[130:131] op_sel_hi:[0,1]
	v_pk_mul_f32 v[104:105], v[102:103], v[104:105] op_sel_hi:[0,1]
	v_pk_mul_f32 v[130:131], v[102:103], v[154:155] op_sel_hi:[0,1]
	v_pk_mul_f32 v[114:115], v[102:103], v[114:115] op_sel_hi:[0,1]
	v_pk_mul_f32 v[132:133], v[102:103], v[134:135] op_sel_hi:[0,1]
	v_pk_mul_f32 v[116:117], v[102:103], v[116:117] op_sel_hi:[0,1]
	v_pk_mul_f32 v[128:129], v[102:103], v[128:129] op_sel_hi:[0,1]
	v_pk_mul_f32 v[72:73], v[102:103], v[72:73] op_sel_hi:[0,1]
	v_pk_fma_f32 v[88:89], v[34:35], v[104:105], v[88:89]
	v_pk_fma_f32 v[86:87], v[36:37], v[122:123], v[86:87]
	v_pk_fma_f32 v[92:93], v[38:39], v[114:115], v[92:93]
	v_pk_fma_f32 v[90:91], v[40:41], v[130:131], v[90:91]
	v_pk_fma_f32 v[96:97], v[42:43], v[116:117], v[96:97]
	v_pk_fma_f32 v[94:95], v[44:45], v[132:133], v[94:95]
	v_pk_fma_f32 v[72:73], v[46:47], v[72:73], v[100:101]
	v_pk_fma_f32 v[98:99], v[48:49], v[128:129], v[98:99]
	v_cvt_pk_bf16_f32 v86, v86, v87
	v_cvt_pk_bf16_f32 v87, v88, v89
	v_cvt_pk_bf16_f32 v88, v90, v91
	v_cvt_pk_bf16_f32 v89, v92, v93
	v_cvt_pk_bf16_f32 v90, v94, v95
	v_cvt_pk_bf16_f32 v91, v96, v97
	v_cvt_pk_bf16_f32 v92, v98, v99
	v_cvt_pk_bf16_f32 v93, v72, v73
	global_store_dwordx2 v[70:71], v[86:87], off
	global_store_dwordx2 v[70:71], v[88:89], off offset:512
	global_store_dwordx2 v[70:71], v[90:91], off offset:1024
	v_lshlrev_b32_e32 v95, 16, v87
	v_lshlrev_b32_e32 v94, 16, v86
	v_and_b32_e32 v87, 0xffff0000, v87
	v_and_b32_e32 v86, 0xffff0000, v86
	v_lshlrev_b32_e32 v97, 16, v89
	v_lshlrev_b32_e32 v96, 16, v88
	v_and_b32_e32 v89, 0xffff0000, v89
	v_and_b32_e32 v88, 0xffff0000, v88
	v_lshlrev_b32_e32 v72, 16, v90
	v_and_b32_e32 v73, 0xffff0000, v90
	global_store_dwordx2 v[70:71], v[92:93], off offset:1536
	v_lshlrev_b32_e32 v70, 16, v92
	v_lshlrev_b32_e32 v90, 16, v91
	v_pk_mul_f32 v[98:99], v[86:87], v[86:87]
	v_pk_mul_f32 v[100:101], v[88:89], v[88:89]
	v_and_b32_e32 v91, 0xffff0000, v91
	v_mul_f32_e32 v71, v72, v72
	v_mul_f32_e32 v105, v73, v73
	v_mul_f32_e32 v102, v90, v90
	v_mov_b32_e32 v104, v70
	v_mov_b32_e32 v116, v94
	v_mov_b32_e32 v117, v86
	v_mov_b32_e32 v86, v95
	v_mov_b32_e32 v122, v96
	v_mov_b32_e32 v123, v88
	v_mov_b32_e32 v88, v97
	v_pk_fma_f32 v[94:95], v[94:95], v[94:95], v[98:99]
	v_pk_fma_f32 v[96:97], v[96:97], v[96:97], v[100:101]
	v_and_b32_e32 v85, 0xffff0000, v92
	v_lshlrev_b32_e32 v92, 16, v93
	v_and_b32_e32 v93, 0xffff0000, v93
	v_pk_fma_f32 v[98:99], v[90:91], v[90:91], v[102:103] op_sel_hi:[1,1,0]
	v_pk_add_f32 v[100:101], v[70:71], v[104:105]
	v_pk_add_f32 v[94:95], v[94:95], v[94:95] op_sel_hi:[0,1]
	v_pk_add_f32 v[96:97], v[96:97], v[96:97] op_sel_hi:[0,1]
	v_mul_f32_e32 v114, v70, v70
	v_mul_f32_e32 v98, v85, v85
	v_mov_b32_e32 v115, v101
	v_mul_f32_e32 v94, v92, v92
	v_mul_f32_e32 v96, v93, v93
	v_pk_add_f32 v[98:99], v[114:115], v[98:99]
	v_pk_add_f32 v[94:95], v[94:95], v[96:97]
	v_mov_b32_e32 v71, v85
	v_pk_add_f32 v[94:95], v[98:99], v[94:95]
	s_nop 0
	v_mov_b32_e32 v127, v94
	v_mov_b32_e32 v94, v103
	v_pk_add_f32 v[94:95], v[126:127], v[94:95]
	ds_bpermute_b32 v97, v69, v95
	ds_bpermute_b32 v96, v69, v94
	s_waitcnt lgkmcnt(0)
	v_pk_add_f32 v[94:95], v[94:95], v[96:97]
	ds_bpermute_b32 v97, v80, v95
	ds_bpermute_b32 v96, v80, v94
	s_waitcnt lgkmcnt(0)
	v_pk_add_f32 v[94:95], v[94:95], v[96:97]
	ds_bpermute_b32 v97, v81, v95
	ds_bpermute_b32 v96, v81, v94
	s_waitcnt lgkmcnt(0)
	v_pk_add_f32 v[94:95], v[94:95], v[96:97]
	ds_bpermute_b32 v97, v82, v95
	ds_bpermute_b32 v96, v82, v94
	s_waitcnt lgkmcnt(0)
	v_pk_add_f32 v[94:95], v[94:95], v[96:97]
	ds_bpermute_b32 v97, v83, v95
	ds_bpermute_b32 v96, v83, v94
	s_waitcnt lgkmcnt(0)
	v_pk_add_f32 v[94:95], v[94:95], v[96:97]
	ds_bpermute_b32 v97, v84, v95
	ds_bpermute_b32 v96, v84, v94
	s_waitcnt lgkmcnt(0)
	v_pk_add_f32 v[94:95], v[94:95], v[96:97]
	s_nop 0
	v_pk_fma_f32 v[94:95], v[94:95], s[20:21], v[68:69] op_sel_hi:[1,0,0]
	s_nop 0
	v_mul_f32_e32 v85, 0x4b800000, v95
	v_mul_f32_e32 v96, 0x4b800000, v94
	v_cmp_gt_f32_e32 vcc, s24, v94
	v_cmp_gt_f32_e64 s[4:5], s24, v95
	s_nop 0
	v_cndmask_b32_e32 v94, v94, v96, vcc
	v_cndmask_b32_e64 v85, v95, v85, s[4:5]
	v_rsq_f32_e32 v85, v85
	v_rsq_f32_e32 v95, v94
	v_mul_f32_e32 v94, 0x45800000, v85
	v_mul_f32_e32 v96, 0x45800000, v95
	v_cndmask_b32_e64 v94, v85, v94, s[4:5]
	v_cndmask_b32_e32 v96, v95, v96, vcc
	v_pk_mul_f32 v[98:99], v[94:95], v[116:117] op_sel_hi:[0,1]
	v_pk_mul_f32 v[86:87], v[94:95], v[86:87] op_sel_hi:[0,1]
	v_pk_mul_f32 v[100:101], v[94:95], v[122:123] op_sel_hi:[0,1]
	v_pk_mul_f32 v[88:89], v[94:95], v[88:89] op_sel_hi:[0,1]
	v_pk_mul_f32 v[72:73], v[94:95], v[72:73] op_sel_hi:[0,1]
	v_pk_mul_f32 v[90:91], v[94:95], v[90:91] op_sel_hi:[0,1]
	v_pk_mul_f32 v[70:71], v[94:95], v[70:71] op_sel_hi:[0,1]
	v_pk_mul_f32 v[92:93], v[94:95], v[92:93] op_sel_hi:[0,1]
	v_pk_mul_f32 v[94:95], v[96:97], v[120:121] op_sel_hi:[0,1]
	v_pk_mul_f32 v[102:103], v[96:97], v[108:109] op_sel_hi:[0,1]
	v_pk_mul_f32 v[104:105], v[96:97], v[142:143] op_sel_hi:[0,1]
	v_pk_mul_f32 v[108:109], v[96:97], v[110:111] op_sel_hi:[0,1]
	v_pk_mul_f32 v[110:111], v[96:97], v[124:125] op_sel_hi:[0,1]
	v_pk_mul_f32 v[112:113], v[96:97], v[112:113] op_sel_hi:[0,1]
	v_pk_mul_f32 v[114:115], v[96:97], v[118:119] op_sel_hi:[0,1]
	v_pk_fma_f32 v[86:87], v[50:51], v[86:87], v[2:3]
	v_pk_fma_f32 v[98:99], v[52:53], v[98:99], v[0:1]
	v_pk_fma_f32 v[30:31], v[34:35], v[102:103], v[30:31]
	v_pk_fma_f32 v[28:29], v[36:37], v[94:95], v[28:29]
	v_pk_fma_f32 v[26:27], v[38:39], v[108:109], v[26:27]
	v_pk_fma_f32 v[24:25], v[40:41], v[104:105], v[24:25]
	v_pk_mul_f32 v[96:97], v[96:97], v[106:107] op_sel_hi:[0,1]
	v_pk_fma_f32 v[88:89], v[54:55], v[88:89], v[6:7]
	v_pk_fma_f32 v[100:101], v[56:57], v[100:101], v[4:5]
	v_pk_fma_f32 v[90:91], v[58:59], v[90:91], v[10:11]
	v_pk_fma_f32 v[72:73], v[60:61], v[72:73], v[8:9]
	v_pk_fma_f32 v[92:93], v[62:63], v[92:93], v[14:15]
	v_pk_fma_f32 v[70:71], v[64:65], v[70:71], v[12:13]
	v_pk_fma_f32 v[22:23], v[42:43], v[112:113], v[22:23]
	v_pk_fma_f32 v[20:21], v[44:45], v[110:111], v[20:21]
	v_pk_fma_f32 v[16:17], v[48:49], v[114:115], v[16:17]
	v_cvt_pk_bf16_f32 v94, v98, v99
	v_cvt_pk_bf16_f32 v95, v86, v87
	v_cvt_pk_bf16_f32 v28, v28, v29
	v_cvt_pk_bf16_f32 v29, v30, v31
	v_cvt_pk_bf16_f32 v24, v24, v25
	v_cvt_pk_bf16_f32 v25, v26, v27
	v_pk_fma_f32 v[18:19], v[46:47], v[96:97], v[18:19]
	v_cvt_pk_bf16_f32 v86, v100, v101
	v_cvt_pk_bf16_f32 v87, v88, v89
	v_cvt_pk_bf16_f32 v72, v72, v73
	v_cvt_pk_bf16_f32 v73, v90, v91
	v_cvt_pk_bf16_f32 v70, v70, v71
	v_cvt_pk_bf16_f32 v71, v92, v93
	v_cvt_pk_bf16_f32 v20, v20, v21
	v_cvt_pk_bf16_f32 v21, v22, v23
	v_cvt_pk_bf16_f32 v16, v16, v17
	global_store_dwordx2 v[76:77], v[94:95], off
	global_store_dwordx2 v[76:77], v[86:87], off offset:512
	global_store_dwordx2 v[76:77], v[72:73], off offset:1024
	global_store_dwordx2 v[76:77], v[70:71], off offset:1536
	global_store_dwordx2 v[78:79], v[28:29], off
	global_store_dwordx2 v[78:79], v[24:25], off offset:512
	global_store_dwordx2 v[78:79], v[20:21], off offset:1024
	v_lshlrev_b32_e32 v23, 16, v29
	v_lshlrev_b32_e32 v22, 16, v28
	v_and_b32_e32 v27, 0xffff0000, v29
	v_and_b32_e32 v26, 0xffff0000, v28
	v_lshlrev_b32_e32 v29, 16, v25
	v_lshlrev_b32_e32 v28, 16, v24
	v_and_b32_e32 v25, 0xffff0000, v25
	v_and_b32_e32 v24, 0xffff0000, v24
	v_cvt_pk_bf16_f32 v17, v18, v19
	v_lshlrev_b32_e32 v18, 16, v20
	v_and_b32_e32 v19, 0xffff0000, v20
	v_lshlrev_b32_e32 v20, 16, v16
	v_lshlrev_b32_e32 v30, 16, v21
	v_pk_mul_f32 v[70:71], v[26:27], v[26:27]
	v_pk_mul_f32 v[72:73], v[24:25], v[24:25]
	global_store_dwordx2 v[78:79], v[16:17], off offset:1536
	v_and_b32_e32 v79, 0xffff0000, v16
	v_and_b32_e32 v31, 0xffff0000, v21
	v_mul_f32_e32 v21, v18, v18
	v_mul_f32_e32 v77, v19, v19
	v_mul_f32_e32 v78, v30, v30
	v_mov_b32_e32 v76, v20
	v_mov_b32_e32 v88, v22
	v_mov_b32_e32 v89, v26
	v_mov_b32_e32 v26, v23
	v_mov_b32_e32 v90, v28
	v_mov_b32_e32 v91, v24
	v_mov_b32_e32 v24, v29
	v_pk_fma_f32 v[22:23], v[22:23], v[22:23], v[70:71]
	v_pk_fma_f32 v[28:29], v[28:29], v[28:29], v[72:73]
	v_lshlrev_b32_e32 v16, 16, v17
	v_and_b32_e32 v17, 0xffff0000, v17
	v_pk_fma_f32 v[70:71], v[30:31], v[30:31], v[78:79] op_sel_hi:[1,1,0]
	v_pk_add_f32 v[72:73], v[20:21], v[76:77]
	v_pk_add_f32 v[22:23], v[22:23], v[22:23] op_sel_hi:[0,1]
	v_pk_add_f32 v[28:29], v[28:29], v[28:29] op_sel_hi:[0,1]
	v_mul_f32_e32 v86, v20, v20
	v_mul_f32_e32 v70, v79, v79
	v_mov_b32_e32 v87, v73
	v_mul_f32_e32 v22, v16, v16
	v_mul_f32_e32 v28, v17, v17
	v_pk_add_f32 v[70:71], v[86:87], v[70:71]
	v_pk_add_f32 v[22:23], v[22:23], v[28:29]
	v_mov_b32_e32 v21, v79
	v_pk_add_f32 v[22:23], v[70:71], v[22:23]
	s_nop 0
	v_add_f32_e32 v22, v22, v23
	ds_bpermute_b32 v23, v69, v22
	s_waitcnt lgkmcnt(0)
	v_add_f32_e32 v22, v22, v23
	ds_bpermute_b32 v23, v80, v22
	s_waitcnt lgkmcnt(0)
	v_add_f32_e32 v22, v22, v23
	ds_bpermute_b32 v23, v81, v22
	s_waitcnt lgkmcnt(0)
	v_add_f32_e32 v22, v22, v23
	ds_bpermute_b32 v23, v82, v22
	s_waitcnt lgkmcnt(0)
	v_add_f32_e32 v22, v22, v23
	ds_bpermute_b32 v23, v83, v22
	s_waitcnt lgkmcnt(0)
	v_add_f32_e32 v22, v22, v23
	ds_bpermute_b32 v23, v84, v22
	s_waitcnt lgkmcnt(0)
	v_add_f32_e32 v22, v22, v23
	v_fmamk_f32 v22, v22, 0x3a800000, v68
	v_mul_f32_e32 v23, 0x4b800000, v22
	v_cmp_gt_f32_e32 vcc, s24, v22
	s_nop 1
	v_cndmask_b32_e32 v22, v22, v23, vcc
	v_rsq_f32_e32 v22, v22
	s_nop 0
	v_mul_f32_e32 v23, 0x45800000, v22
	v_cndmask_b32_e32 v22, v22, v23, vcc
	v_pk_mul_f32 v[28:29], v[22:23], v[88:89] op_sel_hi:[0,1]
	v_pk_mul_f32 v[26:27], v[22:23], v[26:27] op_sel_hi:[0,1]
	v_pk_mul_f32 v[70:71], v[22:23], v[90:91] op_sel_hi:[0,1]
	v_pk_mul_f32 v[24:25], v[22:23], v[24:25] op_sel_hi:[0,1]
	v_pk_mul_f32 v[18:19], v[22:23], v[18:19] op_sel_hi:[0,1]
	v_pk_mul_f32 v[30:31], v[22:23], v[30:31] op_sel_hi:[0,1]
	v_pk_mul_f32 v[20:21], v[22:23], v[20:21] op_sel_hi:[0,1]
	v_pk_mul_f32 v[16:17], v[22:23], v[16:17] op_sel_hi:[0,1]
	v_pk_fma_f32 v[22:23], v[50:51], v[26:27], v[2:3]
	v_pk_fma_f32 v[26:27], v[52:53], v[28:29], v[0:1]
	v_pk_fma_f32 v[24:25], v[54:55], v[24:25], v[6:7]
	v_pk_fma_f32 v[28:29], v[56:57], v[70:71], v[4:5]
	v_pk_fma_f32 v[30:31], v[58:59], v[30:31], v[10:11]
	v_pk_fma_f32 v[18:19], v[60:61], v[18:19], v[8:9]
	v_pk_fma_f32 v[16:17], v[62:63], v[16:17], v[14:15]
	v_pk_fma_f32 v[20:21], v[64:65], v[20:21], v[12:13]
	v_cvt_pk_bf16_f32 v26, v26, v27
	v_cvt_pk_bf16_f32 v27, v22, v23
	v_cvt_pk_bf16_f32 v22, v28, v29
	v_cvt_pk_bf16_f32 v23, v24, v25
	v_cvt_pk_bf16_f32 v18, v18, v19
	v_cvt_pk_bf16_f32 v19, v30, v31
	v_cvt_pk_bf16_f32 v20, v20, v21
	v_cvt_pk_bf16_f32 v21, v16, v17
	global_store_dwordx2 v[74:75], v[26:27], off
	global_store_dwordx2 v[74:75], v[22:23], off offset:512
	global_store_dwordx2 v[74:75], v[18:19], off offset:1024
	global_store_dwordx2 v[74:75], v[20:21], off offset:1536
	s_cbranch_scc1 .LBB0_764
